# XCD-uniformity check after seam 0: table loads issued behind the barrier, consumed after the gain-table fill barrier (latency overlapped)
# speedup vs baseline: 1.0048x; 1.0048x over previous
.LBB0_167:
	s_or_b64 exec, exec, s[8:9]
	s_waitcnt lgkmcnt(0)
	s_barrier
	s_mov_b32 s100, 0
	s_cmpk_lg_u32 s28, 0x100
	s_cbranch_scc1 .Lwb_chk_done
	v_mbcnt_lo_u32_b32 v44, -1, 0
	v_mbcnt_hi_u32_b32 v44, -1, v44
	v_lshlrev_b32_e32 v44, 2, v44
	s_add_u32 s98, s34, 0x8000
	s_addc_u32 s99, s35, 0
	global_load_dword v40, v44, s[98:99] sc1
	global_load_dword v41, v44, s[98:99] offset:256 sc1
	global_load_dword v42, v44, s[98:99] offset:512 sc1
	global_load_dword v43, v44, s[98:99] offset:768 sc1

.LBB0_186:
	s_or_b64 exec, exec, s[12:13]
	s_mov_b64 s[12:13], s[0:1]
	v_mov_b32_e32 v8, v208
	s_cmpk_lt_i32 s2, 0x300
	s_waitcnt lgkmcnt(0)
	s_barrier
	s_cselect_b64 s[14:15], -1, 0
	s_cmpk_lg_u32 s28, 0x100
	s_cbranch_scc1 .Lwb_chk_skip
	s_waitcnt vmcnt(0)
	v_cmp_eq_u32_e32 vcc, v40, v41
	v_cmp_eq_u32_e64 s[98:99], v40, v42
	s_nop 3
	s_and_b64 vcc, vcc, s[98:99]
	v_cmp_eq_u32_e64 s[98:99], v40, v43
	s_nop 3
	s_and_b64 vcc, vcc, s[98:99]
	s_cmp_eq_u64 vcc, exec
	s_cselect_b32 s100, 1, 0
.Lwb_chk_skip:
	s_cmpk_gt_i32 s2, 0x2ff
	v_readfirstlane_b32 s16, v8
	s_cbranch_scc1 .LBB0_188
	s_ashr_i32 s8, s2, 31
	s_lshr_b32 s8, s8, 29
	s_add_i32 s8, s2, s8
	s_ashr_i32 s9, s8, 3
	s_and_b32 s8, s8, -8
	s_sub_i32 s8, s2, s8
	s_cmp_lt_i32 s8, 0
	s_movk_i32 s17, 0x61
	s_cselect_b32 s17, s17, 0x60
	s_mul_i32 s8, s8, s17
	s_add_i32 s8, s8, s9
	s_mul_hi_i32 s9, s8, 0x2aaaaaab
	s_lshr_b32 s17, s9, 31
	s_ashr_i32 s9, s9, 4
	s_add_i32 s9, s9, s17
	s_lshl_b32 s17, s9, 3
	s_mulk_i32 s9, 0x60
	s_sub_i32 s8, s8, s9
	s_bfe_i32 s9, s8, 0x80000
	s_bfe_u32 s9, s9, 0x3000c
	s_add_i32 s9, s8, s9
	s_bfe_i32 s18, s9, 0x80000
	s_and_b32 s9, s9, 0xf8
	s_sub_i32 s8, s8, s9
	s_sext_i32_i16 s18, s18
	s_sext_i32_i8 s8, s8
	s_add_i32 s50, s17, s8
	s_ashr_i32 s8, s18, 3
